# v11 + P4a S3: the 12 distinct MFMA operand fragments read once from LDS (was 24 reads with three exposed round trips per mm2), waits recomputed
# baseline (speedup 1.0000x reference)
; __device__ __forceinline__ unsigned pk2(float lo, float hi) { f32x2_t v = {lo, hi}; bf16x2_t b = __builtin_convertvector(v, bf16x2_t); return __builtin_bit_cast(unsigned, b); }
; __device__ __forceinline__ void chunk_item(const PAArgs& A, unsigned char* lds, int item, int tid, int wave, int lane, const ChunkRaw& RAW) {
;     ...
;     {
;         f32x4 c0 = z4, c1 = z4;
;         const int jb = ti * 16 + fq * 4;
;         const int ta = tj0 * 16 + fr, tb = ta + 16;
;     ...
;         mm2(BT, AT, ti, tj0, fr, fq, c0, c1);
;         { const f32x4 m0 = S3_MASK(c0, ta, 0), m1 = S3_MASK(c1, tb, 0);
;           *(u32x2*)(AABb + ta * MST + jb) = (u32x2){pk2(m0[0], m0[1]), pk2(m0[2], m0[3])}; *(u32x2*)(AABb + tb * MST + jb) = (u32x2){pk2(m1[0], m1[1]), pk2(m1[2], m1[3])};
;           if (tj0 == ti) *(f32x4*)(Dg + (ti * 16 + fr) * 16 + fq * 4) = m0;
;           if (tj0 + 1 == ti) *(f32x4*)(Dg + (ti * 16 + fr) * 16 + fq * 4) = m1; }
.LBB0_431:
	s_waitcnt lgkmcnt(0)
	s_barrier
	ds_read_b128 v[188:191], v52 offset:9216
	ds_read_b128 v[192:195], v53
	ds_read_b128 v[196:199], v53 offset:2304
	ds_read_b128 v[200:203], v52 offset:9280
	ds_read_b128 v[204:207], v53 offset:64
	ds_read_b128 v[208:211], v53 offset:2368
	ds_read_b128 v[212:215], v52 offset:18432
	ds_read_b128 v[216:219], v52 offset:18496
	ds_read_b128 v[220:223], v53 offset:27648
	ds_read_b128 v[224:227], v53 offset:29952
	ds_read_b128 v[228:231], v53 offset:27712
	ds_read_b128 v[232:235], v53 offset:30016
	s_nop 0
	s_nop 0
	s_nop 0
	s_nop 0
	s_nop 0
	s_waitcnt lgkmcnt(10)
	v_mfma_f32_16x16x32_bf16 v[4:7], v[188:191], v[192:195], 0
	v_readlane_b32 s0, v240, 16
	v_readlane_b32 s1, v240, 17
	s_andn2_b64 vcc, exec, s[0:1]
	s_nop 0
	s_waitcnt lgkmcnt(9)
	v_mfma_f32_16x16x32_bf16 v[0:3], v[188:191], v[196:199], 0
	s_nop 0
	s_nop 0
	s_waitcnt lgkmcnt(7)
	v_mfma_f32_16x16x32_bf16 v[4:7], v[200:203], v[204:207], v[4:7]
	s_nop 0
	s_nop 0
	s_waitcnt lgkmcnt(6)
	v_mfma_f32_16x16x32_bf16 v[0:3], v[200:203], v[208:211], v[0:3]
	s_nop 4
	v_cndmask_b32_e64 v4, 0, v4, s[54:55]
	v_cndmask_b32_e64 v5, 0, v5, s[22:23]
	v_cndmask_b32_e64 v6, 0, v6, s[20:21]
	v_cndmask_b32_e64 v7, 0, v7, s[56:57]
	v_cndmask_b32_e64 v0, 0, v0, s[58:59]
	v_cndmask_b32_e64 v1, 0, v1, s[60:61]
	v_cndmask_b32_e64 v2, 0, v2, s[62:63]
	v_cndmask_b32_e64 v3, 0, v3, s[64:65]
	v_cvt_pk_bf16_f32 v18, v4, v5
	v_cvt_pk_bf16_f32 v19, v6, v7
	ds_write_b64 v73, v[18:19]
	v_cvt_pk_bf16_f32 v18, v0, v1
	v_cvt_pk_bf16_f32 v19, v2, v3
	ds_write_b64 v74, v[18:19]
	s_cbranch_vccnz .LBB0_433
	ds_write_b128 v56, v[4:7]

; __device__ __forceinline__ unsigned pk2(float lo, float hi) { f32x2_t v = {lo, hi}; bf16x2_t b = __builtin_convertvector(v, bf16x2_t); return __builtin_bit_cast(unsigned, b); }
; #define LBAR() do { asm volatile("s_waitcnt lgkmcnt(0)" ::: "memory"); __builtin_amdgcn_s_barrier(); asm volatile("" ::: "memory"); } while (0)
; __device__ __forceinline__ void chunk_item(const PAArgs& A, unsigned char* lds, int item, int tid, int wave, int lane, const ChunkRaw& RAW) {
;     ...
;         c0 = z4; c1 = z4; mm2(KT, AT, ti, tj0, fr, fq, c0, c1);
;         { const f32x4 m0 = S3_MASK(c0, ta, 0), m1 = S3_MASK(c1, tb, 0);
;           *(u32x2*)(AAK + ta * MST + jb) = (u32x2){pk2(m0[0], m0[1]), pk2(m0[2], m0[3])}; *(u32x2*)(AAK + tb * MST + jb) = (u32x2){pk2(m1[0], m1[1]), pk2(m1[2], m1[3])}; }
;         c0 = z4; c1 = z4; mm2(BT, RT, ti, tj0, fr, fq, c0, c1);
;         { const f32x4 m0 = S3_MASK(c0, ta, 1), m1 = S3_MASK(c1, tb, 1);
;           *(u32x2*)(ARB + ta * MST + jb) = (u32x2){pk2(m0[0], m0[1]), pk2(m0[2], m0[3])}; *(u32x2*)(ARB + tb * MST + jb) = (u32x2){pk2(m1[0], m1[1]), pk2(m1[2], m1[3])}; }
;         c0 = z4; c1 = z4; mm2(KT, RT, ti, tj0, fr, fq, c0, c1);
;         { const f32x4 m0 = S3_MASK(c0, ta, 1), m1 = S3_MASK(c1, tb, 1);
;           *(u32x2*)(ARK + ta * MST + jb) = (u32x2){pk2(m0[0], m0[1]), pk2(m0[2], m0[3])}; *(u32x2*)(ARK + tb * MST + jb) = (u32x2){pk2(m1[0], m1[1]), pk2(m1[2], m1[3])}; }
;     ...
;     }
;     LBAR();
;     {
;         f32x4 c0 = z4, c1 = z4;
;         mm2(AAK, VT, ti, tj0, fr, fq, c0, c1);
;         *(u32x2*)(AVT + (tj0 * 16 + fr) * MST + ti * 16 + fq * 4) = (u32x2){pk2(c0[0], c0[1]), pk2(c0[2], c0[3])};
;         *(u32x2*)(AVT + (tj0 * 16 + 16 + fr) * MST + ti * 16 + fq * 4) = (u32x2){pk2(c1[0], c1[1]), pk2(c1[2], c1[3])};
.LBB0_435:
	s_nop 0
	s_nop 0
	s_nop 0
	s_nop 0
	s_and_b64 vcc, exec, s[6:7]
	s_nop 0
	s_waitcnt lgkmcnt(7)
	v_mfma_f32_16x16x32_bf16 v[4:7], v[212:215], v[192:195], 0
	s_nop 0
	v_mfma_f32_16x16x32_bf16 v[0:3], v[212:215], v[196:199], 0
	s_nop 0
	s_nop 0
	s_waitcnt lgkmcnt(6)
	v_mfma_f32_16x16x32_bf16 v[4:7], v[216:219], v[204:207], v[4:7]
	s_nop 0
	s_nop 0
	v_mfma_f32_16x16x32_bf16 v[0:3], v[216:219], v[208:211], v[0:3]
	s_nop 4
	v_cndmask_b32_e64 v4, 0, v4, s[54:55]
	v_cndmask_b32_e64 v5, 0, v5, s[22:23]
	v_cndmask_b32_e64 v6, 0, v6, s[20:21]
	v_cndmask_b32_e64 v7, 0, v7, s[56:57]
	v_cndmask_b32_e64 v18, 0, v0, s[58:59]
	v_cndmask_b32_e64 v19, 0, v1, s[60:61]
	v_cndmask_b32_e64 v2, 0, v2, s[62:63]
	v_cndmask_b32_e64 v3, 0, v3, s[64:65]
	v_cvt_pk_bf16_f32 v0, v4, v5
	v_cvt_pk_bf16_f32 v1, v6, v7
	ds_write_b64 v77, v[0:1] offset:64512
	v_cvt_pk_bf16_f32 v0, v18, v19
	v_cvt_pk_bf16_f32 v1, v2, v3
	ds_write_b64 v78, v[0:1] offset:64512
	s_nop 0
	s_nop 0
	s_nop 0
	s_nop 0
	s_nop 0
	s_waitcnt lgkmcnt(7)
	v_mfma_f32_16x16x32_bf16 v[4:7], v[188:191], v[220:223], 0
	s_nop 0
	s_waitcnt lgkmcnt(6)
	v_mfma_f32_16x16x32_bf16 v[0:3], v[188:191], v[224:227], 0
	s_nop 0
	s_nop 0
	s_waitcnt lgkmcnt(5)
	v_mfma_f32_16x16x32_bf16 v[4:7], v[200:203], v[228:231], v[4:7]
	s_nop 0
	s_nop 0
	s_waitcnt lgkmcnt(4)
	v_mfma_f32_16x16x32_bf16 v[0:3], v[200:203], v[232:235], v[0:3]
	s_nop 4
	v_cndmask_b32_e64 v4, v4, 0, s[66:67]
	v_cndmask_b32_e64 v5, 0, v5, s[54:55]
	v_cndmask_b32_e64 v6, v6, 0, s[72:73]
	v_cndmask_b32_e64 v7, v7, 0, s[16:17]
	v_cndmask_b32_e64 v18, 0, v0, s[76:77]
	v_cndmask_b32_e64 v19, 0, v1, s[78:79]
	v_cndmask_b32_e64 v2, 0, v2, s[80:81]
	v_cndmask_b32_e64 v3, 0, v3, s[82:83]
	v_cvt_pk_bf16_f32 v0, v4, v5
	v_cvt_pk_bf16_f32 v1, v6, v7
	ds_write_b64 v83, v[0:1]
	v_cvt_pk_bf16_f32 v0, v18, v19
	v_cvt_pk_bf16_f32 v1, v2, v3
	ds_write_b64 v84, v[0:1]
	s_nop 0
	s_nop 0
	s_nop 0
	s_nop 0
	s_nop 0
	v_mfma_f32_16x16x32_bf16 v[4:7], v[212:215], v[220:223], 0
	s_nop 0
	v_mfma_f32_16x16x32_bf16 v[0:3], v[212:215], v[224:227], 0
	s_nop 0
	s_nop 0
	v_mfma_f32_16x16x32_bf16 v[4:7], v[216:219], v[228:231], v[4:7]
	s_nop 0
	s_nop 0
	v_mfma_f32_16x16x32_bf16 v[0:3], v[216:219], v[232:235], v[0:3]
	s_nop 4
	v_cndmask_b32_e64 v4, v4, 0, s[66:67]
	v_cndmask_b32_e64 v5, 0, v5, s[54:55]
	v_cndmask_b32_e64 v6, v6, 0, s[72:73]
	v_cndmask_b32_e64 v7, v7, 0, s[16:17]
	v_cndmask_b32_e64 v18, 0, v0, s[76:77]
	v_cndmask_b32_e64 v19, 0, v1, s[78:79]
	v_cndmask_b32_e64 v2, 0, v2, s[80:81]
	v_cndmask_b32_e64 v3, 0, v3, s[82:83]
	v_cvt_pk_bf16_f32 v0, v4, v5
	v_cvt_pk_bf16_f32 v1, v6, v7
	ds_write_b64 v85, v[0:1]
	v_cvt_pk_bf16_f32 v0, v18, v19
	v_cvt_pk_bf16_f32 v1, v2, v3
	ds_write_b64 v86, v[0:1]
	s_waitcnt lgkmcnt(0)
	s_barrier
	ds_read_b128 v[0:3], v52 offset:64512
	ds_read_b128 v[4:7], v53 offset:55296
	ds_read_b128 v[18:21], v53 offset:57600
	ds_read_b128 v[116:119], v52 offset:64576
	s_waitcnt lgkmcnt(2)
	v_mfma_f32_16x16x32_bf16 v[4:7], v[0:3], v[4:7], 0
	s_waitcnt lgkmcnt(1)
	v_mfma_f32_16x16x32_bf16 v[0:3], v[0:3], v[18:21], 0
	ds_read_b128 v[18:21], v53 offset:55360
	s_waitcnt lgkmcnt(0)
	v_mfma_f32_16x16x32_bf16 v[4:7], v[116:119], v[18:21], v[4:7]
	ds_read_b128 v[18:21], v53 offset:57664
	s_waitcnt lgkmcnt(0)
	v_mfma_f32_16x16x32_bf16 v[0:3], v[116:119], v[18:21], v[0:3]
	s_nop 4
	v_cvt_pk_bf16_f32 v4, v4, v5
	v_cvt_pk_bf16_f32 v5, v6, v7
	ds_write_b64 v57, v[4:5]
	v_cvt_pk_bf16_f32 v0, v0, v1
	v_cvt_pk_bf16_f32 v1, v2, v3
	ds_write_b64 v57, v[0:1] offset:2304
	s_cbranch_vccnz .LBB0_428
; __device__ __forceinline__ unsigned f2bf(float f) { return pk2(f, f) & 0xffffu; }
; __device__ __forceinline__ void chunk_item(const PAArgs& A, unsigned char* lds, int item, int tid, int wave, int lane, const ChunkRaw& RAW) {
;     ...
;             const int bi = lane >> 4, cc = lane & 15;
;             float t[16];
; #pragma unroll
;             for (int r = 0; r < 16; ++r) {
;                 float acc = (r == cc) ? 1.f : 0.f;
; #pragma unroll
;                 for (int k = 0; k < r; ++k) acc += Dg[(bi * 16 + r) * 16 + k] * t[k];
;                 t[r] = acc;
;             }
; #pragma unroll
;             for (int r = 0; r < 16; ++r) Tinv[(bi * 16 + r) * TST + cc] = (bf16)f2bf(t[r]);
	ds_write_b16 v95, v87
	ds_read_b32 v116, v58 offset:64
	ds_read_b64 v[120:121], v58 offset:128
	ds_read_b96 v[124:126], v58 offset:192
	ds_read_b128 v[128:131], v58 offset:256
	ds_read_b128 v[132:135], v58 offset:320
	ds_read_b32 v136, v58 offset:336
	ds_read_b128 v[140:143], v58 offset:384
	ds_read_b64 v[144:145], v58 offset:400
	ds_read_b128 v[148:151], v58 offset:448
	ds_read_b96 v[152:154], v58 offset:464
	ds_read_b128 v[156:159], v58 offset:512
	ds_read_b128 v[160:163], v58 offset:528
	ds_read_b128 v[164:167], v58 offset:576
	ds_read_b128 v[168:171], v58 offset:592
	ds_read_b32 v172, v58 offset:608
	ds_read_b128 v[176:179], v58 offset:640
	ds_read_b128 v[180:183], v58 offset:656
	ds_read_b64 v[184:185], v58 offset:672
	ds_read_b128 v[188:191], v58 offset:704
	ds_read_b128 v[192:195], v58 offset:720
	ds_read_b96 v[196:198], v58 offset:736
	ds_read_b128 v[200:203], v58 offset:768
	ds_read_b128 v[204:207], v58 offset:784
	ds_read_b128 v[208:211], v58 offset:800
	ds_read_b128 v[212:215], v58 offset:832
	ds_read_b128 v[216:219], v58 offset:848
	ds_read_b128 v[220:223], v58 offset:864
	ds_read_b32 v224, v58 offset:880
	ds_read_b128 v[226:229], v58 offset:896
	ds_read_b128 v[230:233], v58 offset:912
	ds_read_b128 v[234:237], v58 offset:928
	ds_read_b64 v[238:239], v58 offset:944
	s_waitcnt lgkmcnt(15)
	v_fma_f32 v0, v54, v116, v55
	s_waitcnt lgkmcnt(15)
	v_fma_f32 v1, v54, v120, v59
	v_fmac_f32_e32 v1, v0, v121
	s_waitcnt lgkmcnt(15)
	v_fma_f32 v2, v54, v124, v60
	v_fmac_f32_e32 v2, v0, v125
	v_fmac_f32_e32 v2, v1, v126
	s_waitcnt lgkmcnt(15)
	v_fma_f32 v3, v54, v128, v61
	v_fmac_f32_e32 v3, v0, v129
	v_fmac_f32_e32 v3, v1, v130
	v_fmac_f32_e32 v3, v2, v131
	s_waitcnt lgkmcnt(15)
	v_fma_f32 v4, v54, v132, v62
	v_fmac_f32_e32 v4, v0, v133
	v_fmac_f32_e32 v4, v1, v134
	v_fmac_f32_e32 v4, v2, v135
	v_fmac_f32_e32 v4, v3, v136
	s_waitcnt lgkmcnt(15)
	v_fma_f32 v5, v54, v140, v63
	v_fmac_f32_e32 v5, v0, v141
	v_fmac_f32_e32 v5, v1, v142
	v_fmac_f32_e32 v5, v2, v143
	v_fmac_f32_e32 v5, v3, v144
	v_fmac_f32_e32 v5, v4, v145
	s_waitcnt lgkmcnt(15)
	v_fma_f32 v6, v54, v148, v64
	v_fmac_f32_e32 v6, v0, v149
	v_fmac_f32_e32 v6, v1, v150
	v_fmac_f32_e32 v6, v2, v151
	v_fmac_f32_e32 v6, v3, v152
	v_fmac_f32_e32 v6, v4, v153
	v_fmac_f32_e32 v6, v5, v154
	s_waitcnt lgkmcnt(15)
	v_fma_f32 v7, v54, v156, v65
	v_fmac_f32_e32 v7, v0, v157
	v_fmac_f32_e32 v7, v1, v158
	v_fmac_f32_e32 v7, v2, v159
	v_fmac_f32_e32 v7, v3, v160
	v_fmac_f32_e32 v7, v4, v161
	v_fmac_f32_e32 v7, v5, v162
	v_fmac_f32_e32 v7, v6, v163
	s_waitcnt lgkmcnt(15)
	v_fma_f32 v18, v54, v164, v66
	v_fmac_f32_e32 v18, v0, v165
	v_fmac_f32_e32 v18, v1, v166
	v_fmac_f32_e32 v18, v2, v167
	v_fmac_f32_e32 v18, v3, v168
	v_fmac_f32_e32 v18, v4, v169
	v_fmac_f32_e32 v18, v5, v170
	v_fmac_f32_e32 v18, v6, v171
	v_fmac_f32_e32 v18, v7, v172
	s_waitcnt lgkmcnt(14)
	v_fma_f32 v19, v54, v176, v67
	v_fmac_f32_e32 v19, v0, v177
	v_fmac_f32_e32 v19, v1, v178
	v_fmac_f32_e32 v19, v2, v179
	v_fmac_f32_e32 v19, v3, v180
	v_fmac_f32_e32 v19, v4, v181
	v_fmac_f32_e32 v19, v5, v182
	v_fmac_f32_e32 v19, v6, v183
	v_fmac_f32_e32 v19, v7, v184
	v_fmac_f32_e32 v19, v18, v185
	ds_read_b128 v[116:119], v58 offset:960
	ds_read_b128 v[120:123], v58 offset:976
	ds_read_b128 v[124:127], v58 offset:992
	ds_read_b96 v[128:130], v58 offset:1008
	s_waitcnt lgkmcnt(15)
	v_fma_f32 v20, v54, v188, v68
	v_fmac_f32_e32 v20, v0, v189
	v_fmac_f32_e32 v20, v1, v190
	v_fmac_f32_e32 v20, v2, v191
	v_fmac_f32_e32 v20, v3, v192
	v_fmac_f32_e32 v20, v4, v193
	v_fmac_f32_e32 v20, v5, v194
	v_fmac_f32_e32 v20, v6, v195
	v_fmac_f32_e32 v20, v7, v196
	v_fmac_f32_e32 v20, v18, v197
	v_fmac_f32_e32 v20, v19, v198
	s_waitcnt lgkmcnt(12)
	v_fma_f32 v21, v54, v200, v69
	v_fmac_f32_e32 v21, v0, v201
	v_fmac_f32_e32 v21, v1, v202
	v_fmac_f32_e32 v21, v2, v203
	v_fmac_f32_e32 v21, v3, v204
	v_fmac_f32_e32 v21, v4, v205
	v_fmac_f32_e32 v21, v5, v206
	v_fmac_f32_e32 v21, v6, v207
	v_fmac_f32_e32 v21, v7, v208
	v_fmac_f32_e32 v21, v18, v209
	v_fmac_f32_e32 v21, v19, v210
	v_fmac_f32_e32 v21, v20, v211
	s_waitcnt lgkmcnt(8)
	v_fma_f32 v115, v54, v212, v70
	v_fmac_f32_e32 v115, v0, v213
	v_fmac_f32_e32 v115, v1, v214
	v_fmac_f32_e32 v115, v2, v215
	v_fmac_f32_e32 v115, v3, v216
	v_fmac_f32_e32 v115, v4, v217
	v_fmac_f32_e32 v115, v5, v218
	v_fmac_f32_e32 v115, v6, v219
	v_fmac_f32_e32 v115, v7, v220
	v_fmac_f32_e32 v115, v18, v221
	v_fmac_f32_e32 v115, v19, v222
	v_fmac_f32_e32 v115, v20, v223
	v_fmac_f32_e32 v115, v21, v224
	s_waitcnt lgkmcnt(4)
	v_fma_f32 v132, v54, v226, v71
	v_fmac_f32_e32 v132, v0, v227
	v_fmac_f32_e32 v132, v1, v228
	v_fmac_f32_e32 v132, v2, v229
	v_fmac_f32_e32 v132, v3, v230
	v_fmac_f32_e32 v132, v4, v231
	v_fmac_f32_e32 v132, v5, v232
	v_fmac_f32_e32 v132, v6, v233
	v_fmac_f32_e32 v132, v7, v234
	v_fmac_f32_e32 v132, v18, v235
	v_fmac_f32_e32 v132, v19, v236
	v_fmac_f32_e32 v132, v20, v237
	v_fmac_f32_e32 v132, v21, v238
	v_fmac_f32_e32 v132, v115, v239
	s_waitcnt lgkmcnt(0)
	v_fma_f32 v133, v54, v116, v72
	v_fmac_f32_e32 v133, v0, v117
	v_fmac_f32_e32 v133, v1, v118
	v_fmac_f32_e32 v133, v2, v119
	v_fmac_f32_e32 v133, v3, v120
	v_fmac_f32_e32 v133, v4, v121
	v_fmac_f32_e32 v133, v5, v122
	v_fmac_f32_e32 v133, v6, v123
	v_fmac_f32_e32 v133, v7, v124
	v_fmac_f32_e32 v133, v18, v125
	v_fmac_f32_e32 v133, v19, v126
	v_fmac_f32_e32 v133, v20, v127
	v_fmac_f32_e32 v133, v21, v128
	v_fmac_f32_e32 v133, v115, v129
	v_fmac_f32_e32 v133, v132, v130
	v_cvt_pk_bf16_f32 v135, v0, s0
	ds_write_b16 v95, v135 offset:40
	v_cvt_pk_bf16_f32 v134, v1, s0
	ds_write_b16 v95, v134 offset:80
	v_cvt_pk_bf16_f32 v135, v2, s0
	ds_write_b16 v95, v135 offset:120
	v_cvt_pk_bf16_f32 v134, v3, s0
	ds_write_b16 v95, v134 offset:160
	v_cvt_pk_bf16_f32 v135, v4, s0
	ds_write_b16 v95, v135 offset:200
	v_cvt_pk_bf16_f32 v134, v5, s0
	ds_write_b16 v95, v134 offset:240
	v_cvt_pk_bf16_f32 v135, v6, s0
	ds_write_b16 v95, v135 offset:280
	v_cvt_pk_bf16_f32 v134, v7, s0
	ds_write_b16 v95, v134 offset:320
	v_cvt_pk_bf16_f32 v135, v18, s0
	ds_write_b16 v95, v135 offset:360
	v_cvt_pk_bf16_f32 v134, v19, s0
	ds_write_b16 v95, v134 offset:400
	v_cvt_pk_bf16_f32 v135, v20, s0
	ds_write_b16 v95, v135 offset:440
	v_cvt_pk_bf16_f32 v134, v21, s0
	ds_write_b16 v95, v134 offset:480
	v_cvt_pk_bf16_f32 v135, v115, s0
	ds_write_b16 v95, v135 offset:520
	v_cvt_pk_bf16_f32 v134, v132, s0
	ds_write_b16 v95, v134 offset:560
	v_cvt_pk_bf16_f32 v135, v133, s0
	ds_write_b16 v96, v135
	s_branch .LBB0_428
